# attention item: query and gate tiles fetched by coalesced LDS-DMA (128-byte rows) and read from LDS, instead of 16 narrow row-strided loads per lane
# speedup vs baseline: 1.0074x; 1.0074x over previous
; #define ATT_WRITE(IT, HALF) do { _Pragma("unroll") for (int j_ = 0; j_ < TPI; ++j_) { const int t_ = (IT) * TPI + j_; if (t_ < nt) { \
;       char* sl_ = lds + (HALF) * 65536 + j_ * 16384; \
;       *(u32x4*)(sl_ + woff) = rk[j_]; \
;       *(u32x4*)(sl_ + 8192 + woff) = rv[j_]; } } } while (0)
; template <bool NA, bool TRACK>
; DI void attn_item(char* lds, const bf16_t* P, bf16_t* Y, const bf16_t* vt, int rp, int q_off, int k1_off, int nt1,
;                   int vk1, int k2_off, int nt2, int vk2, int g_off, int y_off, int rlo, const float* rpb) {
;     ...
;   bf16x8 qf[4];
; #pragma unroll
;   for (int ks = 0; ks < 4; ++ks) qf[ks] = *(const bf16x8*)(qp + (size_t)(w * 32 + r) * INW + ks * 16 + h * 8);
;   u32x2 gate[2][4];
; #pragma unroll
;   for (int dm = 0; dm < 2; ++dm)
; #pragma unroll
;     for (int g = 0; g < 4; ++g)
;       gate[dm][g] = *(const u32x2*)(P + g_off + (size_t)(w * 32 + r) * INW + dm * 32 + 8 * g + 4 * h);
; #pragma unroll
;   for (int ks = 0; ks < 4; ++ks) asm volatile("" : "+v"(qf[ks]));
; #pragma unroll
;   for (int dm = 0; dm < 2; ++dm)
; #pragma unroll
;     for (int g = 0; g < 4; ++g) asm volatile("" : "+v"(gate[dm][g]));
;   f32x16 o[2];
;   o[0] = zero16(); o[1] = zero16();
;   f32x16 negm;
; #pragma unroll
;   for (int i = 0; i < 16; ++i) negm[i] = 0.f;
;   float l_run = 0.f;
;   constexpr int TPI = 4;
;   const int niter = (nt + TPI - 1) / TPI;
;   u32x4 rk[TPI], rv[TPI];
;     ...
;   ATT_LOAD(0);
;   ATT_WRITE(0, 0);
.LBB0_109:
	s_lshl_b32 s3, s25, 6
	s_add_i32 s12, s3, 0x700
	s_and_b64 s[8:9], s[4:5], exec
	s_cselect_b32 s26, s12, s3
	s_lshl_b32 s10, s10, 6
	s_and_b64 s[8:9], s[4:5], exec
	s_movk_i32 s8, 0x800
	s_cselect_b32 s8, s8, 0x200
	s_add_i32 s13, s8, s10
	s_add_i32 s8, s3, 0xa00
	s_add_i32 s9, s3, 0x300
	s_and_b64 s[4:5], s[4:5], exec
	v_readlane_b32 s36, v254, 41
	s_cselect_b32 s28, s9, s3
	s_cselect_b32 s3, 8, 7
	v_readlane_b32 s46, v254, 51
	v_readlane_b32 s47, v254, 52
	v_readlane_b32 s48, v254, 53
	v_readlane_b32 s49, v254, 54
	s_cselect_b32 s27, s8, s9
	s_cselect_b32 s4, s49, s47
	s_cselect_b32 s5, s48, s46
	s_lshl_b32 s3, s0, s3
	s_add_i32 s3, s3, s10
	s_mul_hi_i32 s9, s3, 0x1200
	s_mulk_i32 s3, 0x1200
	s_add_u32 s8, s5, s3
	s_mul_i32 s0, s0, 0xb0000
	s_addc_u32 s9, s4, s9
	s_add_i32 s0, s0, s13
	s_mul_i32 s3, s11, 0xb00
	s_mulk_i32 s2, 0xb00
	s_add_i32 s10, s0, 0x5800000
	s_lshl_b32 s0, s11, 10
	s_add_i32 s26, s26, s3
	s_add_i32 s12, s13, s2
	s_add_i32 s27, s27, s3
	s_add_i32 s28, s28, s0
	s_andn2_b64 vcc, exec, s[6:7]
	s_mov_b64 s[2:3], -1
	v_readlane_b32 s37, v254, 42
	v_readlane_b32 s38, v254, 43
	v_readlane_b32 s39, v254, 44
	v_readlane_b32 s40, v254, 45
	v_readlane_b32 s41, v254, 46
	v_readlane_b32 s42, v254, 47
	v_readlane_b32 s43, v254, 48
	v_readlane_b32 s44, v254, 49
	v_readlane_b32 s45, v254, 50
	v_readlane_b32 s50, v254, 55
	v_readlane_b32 s51, v254, 56
	s_cbranch_vccz .LBB0_184
	v_readlane_b32 s4, v255, 10
	v_readlane_b32 s5, v255, 11
	s_ashr_i32 s13, s12, 31
	s_ashr_i32 s11, s10, 31
	s_and_b64 vcc, exec, s[4:5]
	s_cbranch_vccz .LBB0_156
	v_readlane_b32 s44, v254, 49
	v_readlane_b32 s45, v254, 50
	s_mov_b32 s34, s26
	s_ashr_i32 s35, s26, 31
	s_lshl_b64 s[34:35], s[34:35], 1
	s_add_u32 s34, s34, s44
	s_addc_u32 s35, s35, s45
	s_mov_b32 s36, s27
	s_ashr_i32 s37, s27, 31
	s_lshl_b64 s[36:37], s[36:37], 1
	s_add_u32 s36, s36, s44
	s_addc_u32 s37, s37, s45
	s_lshl_b64 s[4:5], s[12:13], 1
	s_add_u32 s4, s4, s44
	s_addc_u32 s5, s5, s45
	s_lshl_b64 s[6:7], s[10:11], 1
	s_add_u32 s6, s6, s44
	s_addc_u32 s7, s7, s45
	s_add_i32 s19, s79, 4
	s_lshr_b32 s19, s19, 2
	s_mov_b32 s18, 0
	s_add_u32 s46, s34, 0x2c000
	s_addc_u32 s47, s35, 0
	v_lshrrev_b32_e32 v0, 6, v251
	s_nop 0
	v_readfirstlane_b32 s38, v0
	s_nop 3
	s_lshl_b32 s30, s38, 10
	s_mul_i32 s39, s38, 0x2400
	s_xor_b32 s40, s38, 1
	s_mul_i32 s40, s40, 0x2400
	s_and_b32 s38, s38, 1
	v_bfe_u32 v227, v251, 5, 1
	v_lshrrev_b32_e32 v0, 3, v251
	v_and_b32_e32 v225, 7, v251
	v_bfe_u32 v226, v251, 4, 3
	v_xor_b32_e32 v225, v225, v226
	v_mul_u32_u24_e32 v222, 0x1600, v0
	v_lshl_add_u32 v222, v225, 4, v222
	v_mul_u32_u24_e32 v223, 0x1200, v0
	v_lshl_add_u32 v223, v225, 4, v223
	s_mov_b32 s20, 0
	s_and_b32 s31, s20, 1
	s_lshl_b32 s31, s31, 16
	s_add_u32 s31, s31, s30
	s_lshl_b32 s20, s20, 2
	s_cmp_lt_i32 s20, s79
	s_cselect_b32 s21, 0, s79
	s_cselect_b32 s22, s4, s6
	s_cselect_b32 s23, s5, s7
	s_cselect_b32 s29, s90, 0x800
	s_sub_i32 s20, s20, s21
	s_mul_i32 s21, s20, 0x58000
	s_add_u32 s14, s22, s21
	s_addc_u32 s15, s23, 0
	s_lshl_b32 s20, s20, 6
	s_add_i32 s20, s20, s29
	s_lshl_b32 s20, s20, 1
	s_add_u32 s16, s8, s20
	s_addc_u32 s17, s9, 0
	s_add_u32 m0, s31, 0x0
	s_nop 0
	global_load_lds_dwordx4 v222, s[14:15]
	s_add_u32 m0, s31, 0x2000
	s_nop 0
	global_load_lds_dwordx4 v223, s[16:17]
	s_add_u32 s14, s14, 0x58000
	s_addc_u32 s15, s15, 0
	s_add_u32 s16, s16, 0x80
	s_addc_u32 s17, s17, 0
	s_add_u32 m0, s31, 0x4000
	s_nop 0
	global_load_lds_dwordx4 v222, s[14:15]
	s_add_u32 m0, s31, 0x6000
	s_nop 0
	global_load_lds_dwordx4 v223, s[16:17]
	s_add_u32 s14, s14, 0x58000
	s_addc_u32 s15, s15, 0
	s_add_u32 s16, s16, 0x80
	s_addc_u32 s17, s17, 0
	s_add_u32 m0, s31, 0x8000
	s_nop 0
	global_load_lds_dwordx4 v222, s[14:15]
	s_add_u32 m0, s31, 0xa000
	s_nop 0
	global_load_lds_dwordx4 v223, s[16:17]
	s_add_u32 s14, s14, 0x58000
	s_addc_u32 s15, s15, 0
	s_add_u32 s16, s16, 0x80
	s_addc_u32 s17, s17, 0
	s_add_u32 m0, s31, 0xc000
	s_nop 0
	global_load_lds_dwordx4 v222, s[14:15]
	s_add_u32 m0, s31, 0xe000
	s_nop 0
	global_load_lds_dwordx4 v223, s[16:17]
	s_mov_b64 s[14:15], s[34:35]
	s_mov_b64 s[16:17], s[36:37]
	s_add_u32 m0, s30, 0x10000
	s_nop 0
	global_load_lds_dwordx4 v222, s[14:15]
	s_add_u32 m0, s30, 0x18000
	s_nop 0
	global_load_lds_dwordx4 v222, s[16:17]
	s_add_u32 s14, s14, 0x58000
	s_addc_u32 s15, s15, 0
	s_add_u32 s16, s16, 0x58000
	s_addc_u32 s17, s17, 0
	s_add_u32 m0, s30, 0x12000
	s_nop 0
	global_load_lds_dwordx4 v222, s[14:15]
	s_add_u32 m0, s30, 0x1a000
	s_nop 0
	global_load_lds_dwordx4 v222, s[16:17]
	s_add_u32 s14, s14, 0x58000
	s_addc_u32 s15, s15, 0
	s_add_u32 s16, s16, 0x58000
	s_addc_u32 s17, s17, 0
	s_add_u32 m0, s30, 0x14000
	s_nop 0
	global_load_lds_dwordx4 v222, s[14:15]
	s_add_u32 m0, s30, 0x1c000
	s_nop 0
	global_load_lds_dwordx4 v222, s[16:17]
	s_add_u32 s14, s14, 0x58000
	s_addc_u32 s15, s15, 0
	s_add_u32 s16, s16, 0x58000
	s_addc_u32 s17, s17, 0
	s_add_u32 m0, s30, 0x16000
	s_nop 0
	global_load_lds_dwordx4 v222, s[14:15]
	s_add_u32 m0, s30, 0x1e000
	s_nop 0
	global_load_lds_dwordx4 v222, s[16:17]
; #define ATT_WRITE(IT, HALF) do { _Pragma("unroll") for (int j_ = 0; j_ < TPI; ++j_) { const int t_ = (IT) * TPI + j_; if (t_ < nt) { \
;       char* sl_ = lds + (HALF) * 65536 + j_ * 16384; \
;       *(u32x4*)(sl_ + woff) = rk[j_]; \
;       *(u32x4*)(sl_ + 8192 + woff) = rv[j_]; } } } while (0)
; template <bool NA, bool TRACK>
; DI void attn_item(char* lds, const bf16_t* P, bf16_t* Y, const bf16_t* vt, int rp, int q_off, int k1_off, int nt1,
;                   int vk1, int k2_off, int nt2, int vk2, int g_off, int y_off, int rlo, const float* rpb) {
;     ...
;   bf16x8 qf[4];
; #pragma unroll
;   for (int ks = 0; ks < 4; ++ks) qf[ks] = *(const bf16x8*)(qp + (size_t)(w * 32 + r) * INW + ks * 16 + h * 8);
;   u32x2 gate[2][4];
; #pragma unroll
;   for (int dm = 0; dm < 2; ++dm)
; #pragma unroll
;     for (int g = 0; g < 4; ++g)
;       gate[dm][g] = *(const u32x2*)(P + g_off + (size_t)(w * 32 + r) * INW + dm * 32 + 8 * g + 4 * h);
; #pragma unroll
;   for (int ks = 0; ks < 4; ++ks) asm volatile("" : "+v"(qf[ks]));
; #pragma unroll
;   for (int dm = 0; dm < 2; ++dm)
; #pragma unroll
;     for (int g = 0; g < 4; ++g) asm volatile("" : "+v"(gate[dm][g]));
;   f32x16 o[2];
;   o[0] = zero16(); o[1] = zero16();
;   f32x16 negm;
; #pragma unroll
;   for (int i = 0; i < 16; ++i) negm[i] = 0.f;
;   float l_run = 0.f;
;   constexpr int TPI = 4;
;   const int niter = (nt + TPI - 1) / TPI;
;   u32x4 rk[TPI], rv[TPI];
;     ...
;   ATT_LOAD(0);
;   ATT_WRITE(0, 0);
;   __syncthreads();
;   for (int it = 0; it < niter; ++it) {
;     const int hb = it & 1;
;     if constexpr (NA || TRACK) { if (it + 1 < niter) ATT_LOAD(it + 1); }
;     if constexpr (!NA && !TRACK) {
;     ...
;       const bool more = it + 1 < niter;
;       if (more) ATT_LOAD2(it + 1, 0);
	v_and_b32_e32 v0, 31, v251
	v_lshlrev_b32_e32 v0, 7, v0
	v_bfe_u32 v225, v251, 1, 3
	v_xor_b32_e32 v225, v225, v227
	v_bfe_u32 v226, v251, 6, 1
	v_lshl_or_b32 v228, v226, 12, v0
	v_lshl_or_b32 v216, v225, 4, v228
	v_xor_b32_e32 v229, 2, v225
	v_lshl_or_b32 v217, v229, 4, v228
	v_xor_b32_e32 v229, 4, v225
	v_lshl_or_b32 v218, v229, 4, v228
	v_xor_b32_e32 v229, 6, v225
	v_lshl_or_b32 v219, v229, 4, v228
	v_lshlrev_b32_e32 v226, 2, v226
	v_xor_b32_e32 v225, v225, v226
	v_lshl_or_b32 v220, v225, 4, v0
	v_xor_b32_e32 v229, 2, v225
	v_lshl_or_b32 v221, v229, 4, v0
	v_mov_b32_e32 v2, 0
	v_mov_b32_e32 v3, 0
	v_mov_b32_e32 v4, 0
	v_mov_b32_e32 v5, 0
	v_mov_b32_e32 v6, 0
	v_mov_b32_e32 v7, 0
	v_mov_b32_e32 v8, 0
	v_mov_b32_e32 v9, 0
	v_mov_b32_e32 v10, 0
	v_mov_b32_e32 v11, 0
	v_mov_b32_e32 v12, 0
	v_mov_b32_e32 v13, 0
	v_mov_b32_e32 v14, 0
	v_mov_b32_e32 v15, 0
	v_mov_b32_e32 v16, 0
	v_mov_b32_e32 v17, 0
	v_mov_b32_e32 v18, 0
	v_mov_b32_e32 v19, 0
	v_mov_b32_e32 v20, 0
	v_mov_b32_e32 v21, 0
	v_mov_b32_e32 v22, 0
	v_mov_b32_e32 v23, 0
	v_mov_b32_e32 v24, 0
	v_mov_b32_e32 v25, 0
	v_mov_b32_e32 v26, 0
	v_mov_b32_e32 v27, 0
	v_mov_b32_e32 v28, 0
	v_mov_b32_e32 v29, 0
	v_mov_b32_e32 v30, 0
	v_mov_b32_e32 v31, 0
	v_mov_b32_e32 v32, 0
	v_mov_b32_e32 v33, 0
	v_mov_b32_e32 v34, 0
	v_mov_b32_e32 v35, 0
	v_mov_b32_e32 v36, 0
	v_mov_b32_e32 v37, 0
	v_mov_b32_e32 v38, 0
	v_mov_b32_e32 v39, 0
	v_mov_b32_e32 v40, 0
	v_mov_b32_e32 v41, 0
	v_mov_b32_e32 v42, 0
	v_mov_b32_e32 v43, 0
	v_mov_b32_e32 v44, 0
	v_mov_b32_e32 v45, 0
	v_mov_b32_e32 v46, 0
	v_mov_b32_e32 v47, 0
	v_mov_b32_e32 v48, 0
	v_mov_b32_e32 v49, 0
	v_mov_b32_e32 v50, 0
	v_mov_b32_e32 v51, 0
	v_mov_b32_e32 v52, 0
	v_mov_b32_e32 v53, 0
	v_mov_b32_e32 v54, 0
	v_mov_b32_e32 v55, 0
	v_mov_b32_e32 v56, 0
	v_mov_b32_e32 v57, 0
	v_mov_b32_e32 v58, 0
	v_mov_b32_e32 v59, 0
	v_mov_b32_e32 v60, 0
	v_mov_b32_e32 v61, 0
	v_mov_b32_e32 v62, 0
	v_mov_b32_e32 v63, 0
	v_mov_b32_e32 v64, 0
	v_mov_b32_e32 v65, 0
	v_mov_b32_e32 v212, 0
	v_mov_b32_e32 v213, 0
	v_mov_b32_e32 v214, 0
	v_mov_b32_e32 v215, 0
	s_waitcnt vmcnt(0)
	s_barrier
	v_lshrrev_b32_e32 v0, 7, v251
	v_and_b32_e32 v226, 31, v251
	v_lshlrev_b32_e32 v226, 7, v226
	v_lshl_or_b32 v0, v0, 13, v226
	v_or_b32_e32 v0, 0x10000, v0
	v_bfe_u32 v225, v251, 1, 3
	v_xor_b32_e32 v228, v225, v227
	v_lshl_or_b32 v229, v228, 4, v0
	ds_read_b128 v[130:133], v229
	ds_read_b128 v[146:149], v229 offset:4096
	v_xor_b32_e32 v229, 2, v228
	v_lshl_or_b32 v229, v229, 4, v0
	ds_read_b128 v[134:137], v229
	ds_read_b128 v[150:153], v229 offset:4096
	v_xor_b32_e32 v229, 4, v228
	v_lshl_or_b32 v229, v229, 4, v0
	ds_read_b128 v[138:141], v229
	ds_read_b128 v[154:157], v229 offset:4096
	v_xor_b32_e32 v229, 6, v228
	v_lshl_or_b32 v229, v229, 4, v0
	ds_read_b128 v[142:145], v229
	ds_read_b128 v[158:161], v229 offset:4096
	v_lshrrev_b32_e32 v0, 6, v251
	v_lshl_or_b32 v0, v0, 12, v226
	v_lshl_or_b32 v0, v227, 3, v0
	v_lshl_or_b32 v0, v225, 4, v0
	v_or_b32_e32 v0, 0x18000, v0
	ds_read_b64 v[232:233], v0
	v_xor_b32_e32 v229, 0x10, v0
	ds_read_b64 v[234:235], v229
	v_xor_b32_e32 v229, 0x20, v0
	ds_read_b64 v[236:237], v229
	v_xor_b32_e32 v229, 0x30, v0
	ds_read_b64 v[238:239], v229
	v_xor_b32_e32 v229, 0x40, v0
	ds_read_b64 v[242:243], v229
	v_xor_b32_e32 v229, 0x50, v0
	ds_read_b64 v[244:245], v229
	v_xor_b32_e32 v229, 0x60, v0
	ds_read_b64 v[226:227], v229
	v_xor_b32_e32 v229, 0x70, v0
	ds_read_b64 v[224:225], v229
	s_waitcnt lgkmcnt(0)
	s_barrier
	ds_read_b128 v[162:165], v216
	ds_read_b128 v[166:169], v217
	ds_read_b128 v[170:173], v218
	ds_read_b128 v[174:177], v219
	s_add_i32 s20, s18, 1
	s_cmp_ge_i32 s20, s19
	s_cbranch_scc1 .Ldk_skip_pro
	s_and_b32 s31, s20, 1
	s_lshl_b32 s31, s31, 16
	s_add_u32 s31, s31, s30
	s_lshl_b32 s20, s20, 2
	s_cmp_lt_i32 s20, s79
	s_cselect_b32 s21, 0, s79
	s_cselect_b32 s22, s4, s6
	s_cselect_b32 s23, s5, s7
	s_cselect_b32 s29, s90, 0x800
	s_sub_i32 s20, s20, s21
	s_mul_i32 s21, s20, 0x58000
	s_add_u32 s14, s22, s21
	s_addc_u32 s15, s23, 0
	s_lshl_b32 s20, s20, 6
	s_add_i32 s20, s20, s29
	s_lshl_b32 s20, s20, 1
	s_add_u32 s16, s8, s20
	s_addc_u32 s17, s9, 0
	s_add_u32 m0, s31, 0x0
	s_nop 0
	global_load_lds_dwordx4 v222, s[14:15]
	s_add_u32 m0, s31, 0x2000
	s_nop 0
	global_load_lds_dwordx4 v223, s[16:17]
	s_add_u32 s14, s14, 0x58000
	s_addc_u32 s15, s15, 0
	s_add_u32 s16, s16, 0x80
	s_addc_u32 s17, s17, 0
	s_add_u32 m0, s31, 0x4000
	s_nop 0
	global_load_lds_dwordx4 v222, s[14:15]
	s_add_u32 m0, s31, 0x6000
	s_nop 0
	global_load_lds_dwordx4 v223, s[16:17]
	s_add_u32 s14, s14, 0x58000
	s_addc_u32 s15, s15, 0
	s_add_u32 s16, s16, 0x80
	s_addc_u32 s17, s17, 0
	s_add_u32 m0, s31, 0x8000
	s_nop 0
	global_load_lds_dwordx4 v222, s[14:15]
	s_add_u32 m0, s31, 0xa000
	s_nop 0
	global_load_lds_dwordx4 v223, s[16:17]
	s_add_u32 s14, s14, 0x58000
	s_addc_u32 s15, s15, 0
	s_add_u32 s16, s16, 0x80
	s_addc_u32 s17, s17, 0
	s_add_u32 m0, s31, 0xc000
	s_nop 0
	global_load_lds_dwordx4 v222, s[14:15]
	s_add_u32 m0, s31, 0xe000
	s_nop 0
	global_load_lds_dwordx4 v223, s[16:17]
